# EpiZ boundary steps: drain wait moved from the common else-branch to the end of the rare sequence-start branch
# speedup vs baseline: 1.0190x; 1.0190x over previous
;     __device__ __forceinline__ void operator()(const f32x4 (&acc)[2][2][4][2], const Unit& u, int wr, int wc, int fr, int fq) const {
;     ...
;                     unpk(*(const u32x4*)(V + off), c0a, c0b);
;                     if (s >= 2) { unpk(*(const u32x4*)(V + off - 2048), p1a, p1b); unpk(*(const u32x4*)(V + off - 4096), p2a, p2b); }
;                     else if (s == 1) { unpk(*(const u32x4*)(V + off - 2048), p1a, p1b); p2a = *(const f32x4*)(Vm + 15 * 2048 + ch0); p2b = *(const f32x4*)(Vm + 15 * 2048 + ch0 + 4); }
;                     else { p1a = *(const f32x4*)(Vm + 15 * 2048 + ch0); p1b = *(const f32x4*)(Vm + 15 * 2048 + ch0 + 4); p2a = *(const f32x4*)(Vm + 14 * 2048 + ch0); p2b = *(const f32x4*)(Vm + 14 * 2048 + ch0 + 4); }
.LBB0_511:
	s_or_b64 exec, exec, s[6:7]
	s_waitcnt vmcnt(0)
.LBB0_512:
	s_andn2_saveexec_b64 s[0:1], s[0:1]
	s_cbranch_execz .LBB0_514
	s_movk_i32 s6, 0xe000
	v_add_co_u32_e32 v160, vcc, s6, v202
	global_load_dwordx4 v[156:159], v[202:203], off offset:-4096
	s_nop 0
	v_addc_co_u32_e32 v161, vcc, -1, v203, vcc
	global_load_dwordx4 v[164:167], v[160:161], off
	s_waitcnt vmcnt(1)
	v_lshlrev_b32_e32 v160, 16, v156
	v_and_b32_e32 v161, 0xffff0000, v156
	v_lshlrev_b32_e32 v162, 16, v157
	v_and_b32_e32 v163, 0xffff0000, v157
	v_lshlrev_b32_e32 v156, 16, v158
	v_and_b32_e32 v157, 0xffff0000, v158
	v_lshlrev_b32_e32 v158, 16, v159
	v_and_b32_e32 v159, 0xffff0000, v159
	s_waitcnt vmcnt(0)
	v_lshlrev_b32_e32 v168, 16, v164
	v_and_b32_e32 v169, 0xffff0000, v164
	v_lshlrev_b32_e32 v170, 16, v165
	v_and_b32_e32 v171, 0xffff0000, v165
	v_lshlrev_b32_e32 v164, 16, v166
	v_and_b32_e32 v165, 0xffff0000, v166
	v_lshlrev_b32_e32 v166, 16, v167
	v_and_b32_e32 v167, 0xffff0000, v167

;     __device__ __forceinline__ void operator()(const f32x4 (&acc)[2][2][4][2], const Unit& u, int wr, int wc, int fr, int fq) const {
;     ...
;                     unpk(*(const u32x4*)(V + off), c0a, c0b);
;                     if (s >= 2) { unpk(*(const u32x4*)(V + off - 2048), p1a, p1b); unpk(*(const u32x4*)(V + off - 4096), p2a, p2b); }
;                     else if (s == 1) { unpk(*(const u32x4*)(V + off - 2048), p1a, p1b); p2a = *(const f32x4*)(Vm + 15 * 2048 + ch0); p2b = *(const f32x4*)(Vm + 15 * 2048 + ch0 + 4); }
;                     else { p1a = *(const f32x4*)(Vm + 15 * 2048 + ch0); p1b = *(const f32x4*)(Vm + 15 * 2048 + ch0 + 4); p2a = *(const f32x4*)(Vm + 14 * 2048 + ch0); p2b = *(const f32x4*)(Vm + 14 * 2048 + ch0 + 4); }
.LBB0_519:
	s_or_b64 exec, exec, s[36:37]
	s_waitcnt vmcnt(0)
.LBB0_520:
	s_andn2_saveexec_b64 s[0:1], s[0:1]
	s_cbranch_execz .LBB0_522
	v_add_co_u32_e32 v128, vcc, s25, v156
	global_load_dwordx4 v[124:127], v[156:157], off offset:-4096
	s_nop 0
	v_addc_co_u32_e32 v129, vcc, -1, v157, vcc
	global_load_dwordx4 v[132:135], v[128:129], off
	s_waitcnt vmcnt(1)
	v_lshlrev_b32_e32 v128, 16, v124
	v_and_b32_e32 v129, 0xffff0000, v124
	v_lshlrev_b32_e32 v130, 16, v125
	v_and_b32_e32 v131, 0xffff0000, v125
	v_lshlrev_b32_e32 v124, 16, v126
	v_and_b32_e32 v125, 0xffff0000, v126
	v_lshlrev_b32_e32 v126, 16, v127
	v_and_b32_e32 v127, 0xffff0000, v127
	s_waitcnt vmcnt(0)
	v_lshlrev_b32_e32 v136, 16, v132
	v_and_b32_e32 v137, 0xffff0000, v132
	v_lshlrev_b32_e32 v138, 16, v133
	v_and_b32_e32 v139, 0xffff0000, v133
	v_lshlrev_b32_e32 v132, 16, v134
	v_and_b32_e32 v133, 0xffff0000, v134
	v_lshlrev_b32_e32 v134, 16, v135
	v_and_b32_e32 v135, 0xffff0000, v135

;     __device__ __forceinline__ void operator()(const f32x4 (&acc)[2][2][4][2], const Unit& u, int wr, int wc, int fr, int fq) const {
;     ...
;                     unpk(*(const u32x4*)(V + off), c0a, c0b);
;                     if (s >= 2) { unpk(*(const u32x4*)(V + off - 2048), p1a, p1b); unpk(*(const u32x4*)(V + off - 4096), p2a, p2b); }
;                     else if (s == 1) { unpk(*(const u32x4*)(V + off - 2048), p1a, p1b); p2a = *(const f32x4*)(Vm + 15 * 2048 + ch0); p2b = *(const f32x4*)(Vm + 15 * 2048 + ch0 + 4); }
;                     else { p1a = *(const f32x4*)(Vm + 15 * 2048 + ch0); p1b = *(const f32x4*)(Vm + 15 * 2048 + ch0 + 4); p2a = *(const f32x4*)(Vm + 14 * 2048 + ch0); p2b = *(const f32x4*)(Vm + 14 * 2048 + ch0 + 4); }
.LBB0_527:
	s_or_b64 exec, exec, s[4:5]
	s_waitcnt vmcnt(0)
.LBB0_528:
	s_andn2_saveexec_b64 s[0:1], s[0:1]
	s_cbranch_execz .LBB0_530
	v_add_co_u32_e32 v96, vcc, s27, v124
	global_load_dwordx4 v[92:95], v[124:125], off offset:-4096
	s_nop 0
	v_addc_co_u32_e32 v97, vcc, -1, v125, vcc
	global_load_dwordx4 v[100:103], v[96:97], off
	s_waitcnt vmcnt(1)
	v_lshlrev_b32_e32 v96, 16, v92
	v_and_b32_e32 v97, 0xffff0000, v92
	v_lshlrev_b32_e32 v98, 16, v93
	v_and_b32_e32 v99, 0xffff0000, v93
	v_lshlrev_b32_e32 v92, 16, v94
	v_and_b32_e32 v93, 0xffff0000, v94
	v_lshlrev_b32_e32 v94, 16, v95
	v_and_b32_e32 v95, 0xffff0000, v95
	s_waitcnt vmcnt(0)
	v_lshlrev_b32_e32 v104, 16, v100
	v_and_b32_e32 v105, 0xffff0000, v100
	v_lshlrev_b32_e32 v106, 16, v101
	v_and_b32_e32 v107, 0xffff0000, v101
	v_lshlrev_b32_e32 v100, 16, v102
	v_and_b32_e32 v101, 0xffff0000, v102
	v_lshlrev_b32_e32 v102, 16, v103
	v_and_b32_e32 v103, 0xffff0000, v103

;     __device__ __forceinline__ void operator()(const f32x4 (&acc)[2][2][4][2], const Unit& u, int wr, int wc, int fr, int fq) const {
;     ...
;                     unpk(*(const u32x4*)(V + off), c0a, c0b);
;                     if (s >= 2) { unpk(*(const u32x4*)(V + off - 2048), p1a, p1b); unpk(*(const u32x4*)(V + off - 4096), p2a, p2b); }
;                     else if (s == 1) { unpk(*(const u32x4*)(V + off - 2048), p1a, p1b); p2a = *(const f32x4*)(Vm + 15 * 2048 + ch0); p2b = *(const f32x4*)(Vm + 15 * 2048 + ch0 + 4); }
;                     else { p1a = *(const f32x4*)(Vm + 15 * 2048 + ch0); p1b = *(const f32x4*)(Vm + 15 * 2048 + ch0 + 4); p2a = *(const f32x4*)(Vm + 14 * 2048 + ch0); p2b = *(const f32x4*)(Vm + 14 * 2048 + ch0 + 4); }
.LBB0_536:
	s_andn2_saveexec_b64 s[0:1], s[0:1]
	s_cbranch_execz .LBB0_538
	v_add_co_u32_e32 v40, vcc, s25, v54
	global_load_dwordx4 v[32:35], v[54:55], off offset:-4096
	s_nop 0
	v_addc_co_u32_e32 v41, vcc, -1, v55, vcc
	global_load_dwordx4 v[44:47], v[40:41], off
	s_waitcnt vmcnt(1)
	v_lshlrev_b32_e32 v40, 16, v32
	v_and_b32_e32 v41, 0xffff0000, v32
	v_lshlrev_b32_e32 v42, 16, v33
	v_and_b32_e32 v43, 0xffff0000, v33
	v_lshlrev_b32_e32 v32, 16, v34
	v_and_b32_e32 v33, 0xffff0000, v34
	v_lshlrev_b32_e32 v34, 16, v35
	v_and_b32_e32 v35, 0xffff0000, v35
	s_waitcnt vmcnt(0)
	v_lshlrev_b32_e32 v48, 16, v44
	v_and_b32_e32 v49, 0xffff0000, v44
	v_lshlrev_b32_e32 v50, 16, v45
	v_and_b32_e32 v51, 0xffff0000, v45
	v_lshlrev_b32_e32 v44, 16, v46
	v_and_b32_e32 v45, 0xffff0000, v46
	v_lshlrev_b32_e32 v46, 16, v47
	v_and_b32_e32 v47, 0xffff0000, v47
